# grid barrier: XCD leader bumps the XCD generation word before issuing its own cache invalidate
# baseline (speedup 1.0000x reference)
.LBB0_115:
	s_or_b64 exec, exec, s[6:7]
	s_mov_b64 s[6:7], exec
	v_mbcnt_lo_u32_b32 v0, s6, 0
	v_mbcnt_hi_u32_b32 v0, s7, v0
	v_cmp_eq_u32_e32 vcc, 0, v0
	s_waitcnt vmcnt(0)
	s_and_saveexec_b64 s[8:9], vcc
	s_cbranch_execz .LBB0_117
	s_bcnt1_i32_b64 s6, s[6:7]
	v_mov_b32_e32 v0, 0x2000
	v_mov_b32_e32 v1, s6
	global_atomic_add v0, v1, s[4:5] offset:1024
.LBB0_117:
	s_or_b64 exec, exec, s[8:9]
	buffer_inv sc1
	s_waitcnt vmcnt(0)

.LBB0_174:
	s_or_b64 exec, exec, s[4:5]
	s_mov_b64 s[4:5], exec
	v_mbcnt_lo_u32_b32 v0, s4, 0
	v_mbcnt_hi_u32_b32 v0, s5, v0
	v_cmp_eq_u32_e32 vcc, 0, v0
	s_waitcnt vmcnt(0)
	s_and_saveexec_b64 s[6:7], vcc
	s_cbranch_execz .LBB0_176
	s_bcnt1_i32_b64 s4, s[4:5]
	v_mov_b32_e32 v0, 0x2000
	v_mov_b32_e32 v1, s4
	global_atomic_add v0, v1, s[2:3] offset:1024
.LBB0_176:
	s_or_b64 exec, exec, s[6:7]
	buffer_inv sc1
	s_waitcnt vmcnt(0)
